# retention: vmcnt waits on prefetched tiles no longer force the just-issued gate loads (step-dependent counted ladder), on top of v5
# baseline (speedup 1.0000x reference)
; #define LAS __attribute__((address_space(3)))
; __device__ __forceinline__ unsigned cvt_pk_bf16(float lo, float hi) { unsigned r; asm volatile("v_cvt_pk_bf16_f32 %0, %1, %2" : "=v"(r) : "v"(lo), "v"(hi)); return r; }
; __device__ __forceinline__ void retention_item(LAS unsigned char* lds, const Params& p, int item) {
;     ...
; #pragma unroll
;         for (int db = 0; db < 4; ++db) accSt[db] = accSt[db] * decayC;
; #pragma unroll
;         for (int kh = 0; kh < 2; ++kh) {
;             bf16x8 a[2], bb[2][4];
; #pragma unroll
;             for (int q = 0; q < 2; ++q) { const int ks = 2 * kh + q; a[q] = *(const LAS bf16x8*)(Vts + (16 * wid + fr) * 136 + 32 * ks + 8 * fq);
; #pragma unroll
;                 for (int db = 0; db < 4; ++db) bb[q][db] = *(const LAS bf16x8*)(Kzs + (16 * db + fr) * 136 + 32 * ks + 8 * fq); }
;             __builtin_amdgcn_sched_barrier(0);
; #pragma unroll
;             for (int q = 0; q < 2; ++q)
; #pragma unroll
;                 for (int db = 0; db < 4; ++db) accSt[db] = __builtin_amdgcn_mfma_f32_16x16x32_bf16(a[q], bb[q][db], accSt[db], 0, 0, 0);
;             __builtin_amdgcn_sched_barrier(0);
;         }
;         __syncthreads();
; #pragma unroll
;         for (int db = 0; db < 4; ++db)
; #pragma unroll
;             for (int r = 0; r < 4; ++r) Sts[(16 * wid + 4 * fq + r) * 72 + 16 * db + fr] = (bf16_t)(cvt_pk_bf16(accSt[db][r], 0.f) & 0xffffu);
.LBB0_774:
	v_add_u32_e32 v96, v128, v193
	ds_read_b128 v[56:59], v136 offset:18432
	ds_read_b128 v[60:63], v96 offset:53248
	ds_read_b128 v[64:67], v96 offset:57600
	ds_read_b128 v[68:71], v96 offset:61952
	ds_read_b128 v[72:75], v211 offset:61952
	ds_read_b128 v[76:79], v136 offset:18496
	ds_read_b128 v[80:83], v96 offset:53312
	ds_read_b128 v[84:87], v96 offset:57664
	ds_read_b128 v[88:91], v96 offset:62016
	ds_read_b128 v[92:95], v211 offset:62016
	v_mov_b32_e32 v113, v112
	v_pk_mul_f32 v[42:43], v[112:113], v[42:43]
	v_pk_mul_f32 v[40:41], v[134:135], v[40:41]
	v_pk_mul_f32 v[34:35], v[112:113], v[34:35]
	v_pk_mul_f32 v[32:33], v[134:135], v[32:33]
	v_pk_mul_f32 v[38:39], v[112:113], v[38:39]
	v_pk_mul_f32 v[36:37], v[134:135], v[36:37]
	v_pk_mul_f32 v[46:47], v[112:113], v[46:47]
	v_pk_mul_f32 v[44:45], v[134:135], v[44:45]
	s_waitcnt lgkmcnt(8)
	v_mfma_f32_16x16x32_bf16 v[40:43], v[56:59], v[60:63], v[40:43]
	s_waitcnt lgkmcnt(7)
	v_mfma_f32_16x16x32_bf16 v[32:35], v[56:59], v[64:67], v[32:35]
	s_waitcnt lgkmcnt(6)
	v_mfma_f32_16x16x32_bf16 v[36:39], v[56:59], v[68:71], v[36:39]
	s_waitcnt lgkmcnt(5)
	v_mfma_f32_16x16x32_bf16 v[44:47], v[56:59], v[72:75], v[44:47]
	s_waitcnt lgkmcnt(3)
	v_mfma_f32_16x16x32_bf16 v[40:43], v[76:79], v[80:83], v[40:43]
	s_waitcnt lgkmcnt(2)
	v_mfma_f32_16x16x32_bf16 v[32:35], v[76:79], v[84:87], v[32:35]
	s_waitcnt lgkmcnt(1)
	v_mfma_f32_16x16x32_bf16 v[36:39], v[76:79], v[88:91], v[36:39]
	s_waitcnt lgkmcnt(0)
	v_mfma_f32_16x16x32_bf16 v[44:47], v[76:79], v[92:95], v[44:47]
	ds_read_b128 v[56:59], v136 offset:18560
	ds_read_b128 v[60:63], v136 offset:18624
	ds_read_b128 v[64:67], v96 offset:53376
	ds_read_b128 v[68:71], v96 offset:53440
	ds_read_b128 v[72:75], v96 offset:57728
	ds_read_b128 v[76:79], v96 offset:57792
	ds_read_b128 v[80:83], v96 offset:62080
	ds_read_b128 v[84:87], v96 offset:62144
	ds_read_b128 v[88:91], v211 offset:62080
	ds_read_b128 v[92:95], v211 offset:62144
	s_waitcnt lgkmcnt(7)
	v_mfma_f32_16x16x32_bf16 v[40:43], v[56:59], v[64:67], v[40:43]
	s_waitcnt lgkmcnt(5)
	v_mfma_f32_16x16x32_bf16 v[32:35], v[56:59], v[72:75], v[32:35]
	s_waitcnt lgkmcnt(3)
	v_mfma_f32_16x16x32_bf16 v[36:39], v[56:59], v[80:83], v[36:39]
	s_waitcnt lgkmcnt(1)
	v_mfma_f32_16x16x32_bf16 v[44:47], v[56:59], v[88:91], v[44:47]
	v_mfma_f32_16x16x32_bf16 v[40:43], v[60:63], v[68:71], v[40:43]
	v_mfma_f32_16x16x32_bf16 v[32:35], v[60:63], v[76:79], v[32:35]
	v_mfma_f32_16x16x32_bf16 v[36:39], v[60:63], v[84:87], v[36:39]
	s_waitcnt lgkmcnt(0)
	v_mfma_f32_16x16x32_bf16 v[44:47], v[60:63], v[92:95], v[44:47]
	s_barrier
	v_cvt_pk_bf16_f32 v56, v40, v109
	ds_write_b16 v212, v56
	v_cvt_pk_bf16_f32 v56, v41, v109
	ds_write_b16 v212, v56 offset:144
	v_cvt_pk_bf16_f32 v56, v42, v109
	ds_write_b16 v212, v56 offset:288
	v_cvt_pk_bf16_f32 v56, v43, v109
	ds_write_b16 v212, v56 offset:432
	v_cvt_pk_bf16_f32 v56, v32, v109
	ds_write_b16 v212, v56 offset:32
	v_cvt_pk_bf16_f32 v56, v33, v109
	ds_write_b16 v212, v56 offset:176
	v_cvt_pk_bf16_f32 v56, v34, v109
	ds_write_b16 v212, v56 offset:320
	v_cvt_pk_bf16_f32 v56, v35, v109
	ds_write_b16 v212, v56 offset:464
	v_cvt_pk_bf16_f32 v56, v36, v109
	ds_write_b16 v212, v56 offset:64
	v_cvt_pk_bf16_f32 v56, v37, v109
	ds_write_b16 v212, v56 offset:208
	v_cvt_pk_bf16_f32 v56, v38, v109
	ds_write_b16 v212, v56 offset:352
	v_cvt_pk_bf16_f32 v56, v39, v109
	ds_write_b16 v212, v56 offset:496
	v_cvt_pk_bf16_f32 v56, v44, v109
	ds_write_b16 v212, v56 offset:96
	v_cvt_pk_bf16_f32 v56, v45, v109
	ds_write_b16 v212, v56 offset:240
	v_cvt_pk_bf16_f32 v56, v46, v109
	ds_write_b16 v212, v56 offset:384
	v_cvt_pk_bf16_f32 v56, v47, v109
	ds_write_b16 v212, v56 offset:528
	s_add_i32 s94, s94, -1
	s_add_i32 s95, s95, 1
	s_waitcnt vmcnt(14)
	v_mov_b64_e32 v[58:59], v[54:55]
	v_mov_b64_e32 v[62:63], v[50:51]
	s_cmpk_lg_i32 s94, 0xffee
	v_mov_b64_e32 v[56:57], v[52:53]
	v_mov_b64_e32 v[60:61], v[48:49]
	s_cbranch_scc0 .LBB0_772

; #define LAS __attribute__((address_space(3)))
; __device__ __forceinline__ void retention_item(LAS unsigned char* lds, const Params& p, int item) {
;     ...
;         const RetStep cur = ret_step(p, step, b, dir);
;         if (!cur.isctx) {
; #pragma unroll
;             for (int q = 0; q < 2; ++q) { const int pc = tid + q * 512, row = pc >> 3, seg = pc & 7; *(LAS u32x4*)(Ks + row * 72 + seg * 8) = pk[q]; }
;         }
; #pragma unroll
;         for (int q = 0; q < 4; ++q) { const int pc = tid + q * 512, row = pc >> 4, seg = pc & 15; *(LAS u32x4*)(Vts + row * 136 + seg * 8) = pv[q]; }
; #pragma unroll
;         for (int q = 0; q < 2; ++q) { const int pc = tid + q * 512, row = pc >> 4, seg = pc & 15; *(LAS u32x4*)(Kzs + row * 136 + seg * 8) = pz[q]; }
.LBB0_779:
	s_cmpk_lg_i32 s94, 0xffef
	s_cselect_b64 s[92:93], -1, 0
	s_cmpk_eq_i32 s94, 0xffef
	s_mov_b64 vcc, s[80:81]
	s_cbranch_vccnz .Lret_ladder_relaxed
	s_waitcnt vmcnt(5)
	ds_write_b128 v206, v[0:3] offset:18432
	s_waitcnt vmcnt(4)
	ds_write_b128 v207, v[4:7] offset:18432
	s_waitcnt vmcnt(3)
	ds_write_b128 v208, v[8:11] offset:18432
	s_waitcnt vmcnt(2)
	ds_write_b128 v209, v[12:15] offset:18432
	s_waitcnt vmcnt(1)
	ds_write_b128 v206, v[16:19] offset:53248
	s_waitcnt vmcnt(0)
	ds_write_b128 v207, v[20:23] offset:53248
	s_branch .Lret_ladder_done
.Lret_ladder_relaxed:
	s_waitcnt vmcnt(13)
	ds_write_b128 v206, v[0:3] offset:18432
	s_waitcnt vmcnt(12)
	ds_write_b128 v207, v[4:7] offset:18432
	s_waitcnt vmcnt(11)
	ds_write_b128 v208, v[8:11] offset:18432
	s_waitcnt vmcnt(10)
	ds_write_b128 v209, v[12:15] offset:18432
	s_waitcnt vmcnt(9)
	ds_write_b128 v206, v[16:19] offset:53248
	s_waitcnt vmcnt(8)
	ds_write_b128 v207, v[20:23] offset:53248
.Lret_ladder_done:
	s_cbranch_scc1 .LBB0_784
	s_cmp_lg_u32 s94, 0
	s_cselect_b64 vcc, -1, 0
	s_cmp_eq_u32 s94, 0
	s_cbranch_scc1 .LBB0_785
	s_add_i32 s82, s95, -1
	s_add_i32 s83, s94, 16
	s_and_b64 s[80:81], s[2:3], exec
	s_cselect_b32 s80, s82, s83
	s_lshl_b32 s80, s80, 7
	s_add_u32 s82, s88, s80
	s_addc_u32 s83, s89, 0
	s_mov_b64 s[80:81], 0x10000
	s_mov_b64 s[84:85], 0x2bc00000
	s_mov_b64 s[96:97], 0x2fc00000
	s_branch .LBB0_786
